# scan producer loops: global_load_dword switched to saddr form, 108 64-bit VALU address adds removed
# baseline (speedup 1.0000x reference)
.LBB0_555:
	s_add_i32 s1, s18, 2
	s_min_u32 s16, s1, 7
	s_mul_i32 s16, s16, s57
	s_add_i32 s16, s16, s58
	s_ashr_i32 s17, s16, 31
	s_lshl_b64 s[20:21], s[16:17], 13
	s_add_u32 s22, s20, s61
	s_addc_u32 s23, s21, 0
	s_lshl_b64 s[22:23], s[22:23], 1
	s_add_u32 s22, s26, s22
	s_addc_u32 s23, s27, s23
	s_add_u32 s24, s20, s70
	s_addc_u32 s25, s21, 0
	s_lshl_b64 s[24:25], s[24:25], 1
	s_add_u32 s24, s26, s24
	s_addc_u32 s25, s27, s25
	s_add_u32 s20, s20, s96
	s_addc_u32 s21, s21, 0
	s_lshl_b64 s[20:21], s[20:21], 1
	s_mul_hi_i32 s17, s0, s16
	s_mul_i32 s16, s0, s16
	s_add_u32 s16, s54, s16
	s_addc_u32 s17, s55, s17
	global_load_dword v119, v144, s[16:17]
	global_load_dword v118, v36, s[22:23]
	global_load_dword v117, v36, s[24:25]
	global_load_dword v120, v32, s[16:17]
	global_load_dword v116, v34, s[22:23]
	global_load_dword v115, v34, s[24:25]
	global_load_dword v121, v28, s[16:17]
	global_load_dword v114, v30, s[22:23]
	global_load_dword v113, v30, s[24:25]
	global_load_dword v122, v24, s[16:17]
	global_load_dword v112, v26, s[22:23]
	global_load_dword v111, v26, s[24:25]
	global_load_dword v123, v20, s[16:17]
	global_load_dword v110, v22, s[22:23]
	global_load_dword v109, v22, s[24:25]
	global_load_dword v124, v16, s[16:17]
	global_load_dword v108, v18, s[22:23]
	global_load_dword v107, v18, s[24:25]
	global_load_dword v125, v12, s[16:17]
	global_load_dword v106, v14, s[22:23]
	global_load_dword v105, v14, s[24:25]
	global_load_dword v126, v8, s[16:17]
	s_add_u32 s16, s26, s20
	v_lshl_add_u64 v[38:39], s[22:23], 0, v[10:11]
	s_addc_u32 s17, s27, s21
	global_load_dword v104, v[38:39], off
	global_load_dword v103, v10, s[24:25]
	global_load_dword v99, v6, s[16:17]
	global_load_dword v100, v4, s[16:17]
	global_load_dword v101, v2, s[16:17]
	global_load_dword v102, v0, s[16:17]
	s_waitcnt vmcnt(55)
	v_lshlrev_b32_e32 v38, 16, v62
	v_and_b32_e32 v39, 0xffff0000, v62
	v_pk_fma_f32 v[56:57], v[38:39], s[66:67], 0 op_sel_hi:[1,0,0]
	s_waitcnt vmcnt(52)
	v_lshlrev_b32_e32 v38, 16, v65
	v_and_b32_e32 v39, 0xffff0000, v65
	v_pk_fma_f32 v[54:55], v[38:39], s[66:67], v[56:57] op_sel_hi:[1,0,1]
	s_waitcnt vmcnt(49)
	v_lshlrev_b32_e32 v38, 16, v68
	v_and_b32_e32 v39, 0xffff0000, v68
	v_pk_fma_f32 v[52:53], v[38:39], s[66:67], v[54:55] op_sel_hi:[1,0,1]
	s_waitcnt vmcnt(46)
	v_lshlrev_b32_e32 v38, 16, v71
	v_and_b32_e32 v39, 0xffff0000, v71
	v_pk_fma_f32 v[50:51], v[38:39], s[66:67], v[52:53] op_sel_hi:[1,0,1]
	s_waitcnt vmcnt(43)
	v_lshlrev_b32_e32 v38, 16, v74
	v_and_b32_e32 v39, 0xffff0000, v74
	v_pk_fma_f32 v[48:49], v[38:39], s[66:67], v[50:51] op_sel_hi:[1,0,1]
	s_waitcnt vmcnt(40)
	v_lshlrev_b32_e32 v38, 16, v77
	v_and_b32_e32 v39, 0xffff0000, v77
	v_pk_fma_f32 v[46:47], v[38:39], s[66:67], v[48:49] op_sel_hi:[1,0,1]
	s_waitcnt vmcnt(37)
	v_lshlrev_b32_e32 v38, 16, v80
	v_and_b32_e32 v39, 0xffff0000, v80
	v_pk_fma_f32 v[44:45], v[38:39], s[66:67], v[46:47] op_sel_hi:[1,0,1]
	s_waitcnt vmcnt(34)
	v_lshlrev_b32_e32 v38, 16, v85
	v_and_b32_e32 v39, 0xffff0000, v85
	v_pk_fma_f32 v[40:41], v[38:39], s[66:67], v[44:45] op_sel_hi:[1,0,1]
	ds_bpermute_b32 v60, v81, v40
	ds_bpermute_b32 v61, v81, v41
	s_waitcnt lgkmcnt(0)
	v_pk_add_f32 v[38:39], v[40:41], v[60:61]
	ds_bpermute_b32 v58, v82, v38
	ds_bpermute_b32 v59, v82, v39
	s_waitcnt lgkmcnt(0)
	v_pk_add_f32 v[42:43], v[38:39], v[58:59]
	s_nop 0
	v_exp_f32_e32 v38, v42
	s_and_saveexec_b64 s[16:17], s[10:11]
	s_xor_b64 s[16:17], exec, s[16:17]
	s_or_saveexec_b64 s[16:17], s[16:17]
	v_exp_f32_e32 v42, v43
	s_xor_b64 exec, exec, s[16:17]
	v_mov_b32_e32 v128, v38
	v_mov_b32_e32 v129, v42
	ds_write_b64 v96, v[128:129]
	s_or_b64 exec, exec, s[16:17]
	v_pk_add_f32 v[60:61], v[60:61], 0 op_sel_hi:[1,0]
	v_lshlrev_b32_e32 v128, 16, v63
	v_cndmask_b32_e64 v61, v61, 0, s[12:13]
	v_cndmask_b32_e64 v60, v60, 0, s[12:13]
	v_pk_add_f32 v[58:59], v[60:61], v[58:59]
	v_and_b32_e32 v129, 0xffff0000, v63
	v_cndmask_b32_e64 v59, v59, v61, s[14:15]
	v_cndmask_b32_e64 v58, v58, v60, s[14:15]
	v_pk_add_f32 v[56:57], v[56:57], v[58:59]
	v_pk_add_f32 v[54:55], v[54:55], v[58:59]
	v_exp_f32_e32 v60, v56
	v_exp_f32_e32 v61, v57
	v_min_f32_e64 v43, -v56, s33
	v_exp_f32_e32 v56, v43
	v_min_f32_e64 v43, -v57, s33
	v_exp_f32_e32 v57, v43
	v_pk_mul_f32 v[60:61], v[60:61], v[128:129]
	v_lshlrev_b32_e32 v128, 16, v64
	v_cvt_pk_bf16_f32 v43, v60, v61
	v_exp_f32_e32 v60, v54
	v_min_f32_e64 v54, -v54, s33
	v_exp_f32_e32 v61, v55
	v_min_f32_e64 v55, -v55, s33
	v_exp_f32_e32 v54, v54
	v_exp_f32_e32 v55, v55
	v_and_b32_e32 v129, 0xffff0000, v64
	v_pk_mul_f32 v[56:57], v[56:57], v[128:129]
	v_lshlrev_b32_e32 v128, 16, v66
	v_and_b32_e32 v129, 0xffff0000, v66
	v_pk_mul_f32 v[60:61], v[60:61], v[128:129]
	v_lshlrev_b32_e32 v128, 16, v67
	v_and_b32_e32 v129, 0xffff0000, v67
	v_pk_mul_f32 v[54:55], v[54:55], v[128:129]
	v_cvt_pk_bf16_f32 v127, v56, v57
	v_mov_b32_e32 v128, v56
	v_mov_b32_e32 v56, v57
	v_mov_b32_e32 v57, v55
	v_cvt_pk_bf16_f32 v60, v60, v61
	v_add_u32_e32 v61, 0x8000, v97
	v_pk_add_f32 v[52:53], v[52:53], v[58:59]
	v_mov_b32_e32 v129, v54
	v_pk_mul_f32 v[56:57], v[42:43], v[56:57] op_sel_hi:[0,1]
	ds_write2_b32 v61, v43, v60 offset0:128 offset1:196
	v_cvt_pk_bf16_f32 v43, v54, v55
	v_exp_f32_e32 v54, v52
	v_exp_f32_e32 v55, v53
	v_add_u32_e32 v130, 0xa400, v97
	ds_write2_b32 v130, v127, v43 offset1:68
	v_min_f32_e64 v43, -v52, s33
	v_exp_f32_e32 v52, v43
	v_min_f32_e64 v43, -v53, s33
	v_lshlrev_b32_e32 v60, 16, v69
	v_and_b32_e32 v61, 0xffff0000, v69
	v_exp_f32_e32 v53, v43
	v_pk_mul_f32 v[54:55], v[54:55], v[60:61]
	v_pk_add_f32 v[50:51], v[50:51], v[58:59]
	v_cvt_pk_bf16_f32 v43, v54, v55
	v_exp_f32_e32 v54, v50
	v_min_f32_e64 v50, -v50, s33
	v_exp_f32_e32 v55, v51
	v_min_f32_e64 v51, -v51, s33
	v_exp_f32_e32 v50, v50
	v_exp_f32_e32 v51, v51
	v_lshlrev_b32_e32 v60, 16, v70
	v_and_b32_e32 v61, 0xffff0000, v70
	v_pk_mul_f32 v[52:53], v[52:53], v[60:61]
	v_lshlrev_b32_e32 v60, 16, v72
	v_and_b32_e32 v61, 0xffff0000, v72
	v_pk_mul_f32 v[54:55], v[54:55], v[60:61]
	v_lshlrev_b32_e32 v60, 16, v73
	v_and_b32_e32 v61, 0xffff0000, v73
	v_pk_mul_f32 v[50:51], v[50:51], v[60:61]
	v_cvt_pk_bf16_f32 v127, v52, v53
	v_mov_b32_e32 v60, v52
	v_mov_b32_e32 v52, v53
	v_mov_b32_e32 v53, v51
	v_cvt_pk_bf16_f32 v54, v54, v55
	v_add_u32_e32 v131, 0x8400, v97
	v_pk_add_f32 v[48:49], v[48:49], v[58:59]
	v_mov_b32_e32 v61, v50
	v_pk_mul_f32 v[52:53], v[42:43], v[52:53] op_sel_hi:[0,1]
	ds_write2_b32 v131, v43, v54 offset0:8 offset1:76
	v_cvt_pk_bf16_f32 v43, v50, v51
	v_exp_f32_e32 v50, v48
	v_exp_f32_e32 v51, v49
	ds_write2_b32 v130, v127, v43 offset0:136 offset1:204
	v_min_f32_e64 v43, -v48, s33
	v_exp_f32_e32 v48, v43
	v_min_f32_e64 v43, -v49, s33
	v_lshlrev_b32_e32 v54, 16, v75
	v_and_b32_e32 v55, 0xffff0000, v75
	v_exp_f32_e32 v49, v43
	v_pk_mul_f32 v[50:51], v[50:51], v[54:55]
	v_pk_add_f32 v[46:47], v[46:47], v[58:59]
	v_cvt_pk_bf16_f32 v43, v50, v51
	v_exp_f32_e32 v50, v46
	v_min_f32_e64 v46, -v46, s33
	v_exp_f32_e32 v51, v47
	v_min_f32_e64 v47, -v47, s33
	v_exp_f32_e32 v46, v46
	v_exp_f32_e32 v47, v47
	v_lshlrev_b32_e32 v54, 16, v76
	v_and_b32_e32 v55, 0xffff0000, v76
	v_pk_mul_f32 v[48:49], v[48:49], v[54:55]
	v_lshlrev_b32_e32 v54, 16, v78
	v_and_b32_e32 v55, 0xffff0000, v78
	v_pk_mul_f32 v[50:51], v[50:51], v[54:55]
	v_lshlrev_b32_e32 v54, 16, v79
	v_and_b32_e32 v55, 0xffff0000, v79
	v_pk_mul_f32 v[46:47], v[46:47], v[54:55]
	v_cvt_pk_bf16_f32 v127, v48, v49
	v_mov_b32_e32 v54, v48
	v_mov_b32_e32 v48, v49
	v_mov_b32_e32 v49, v47
	v_cvt_pk_bf16_f32 v50, v50, v51
	v_pk_add_f32 v[44:45], v[44:45], v[58:59]
	v_mov_b32_e32 v55, v46
	v_pk_mul_f32 v[48:49], v[42:43], v[48:49] op_sel_hi:[0,1]
	ds_write2_b32 v131, v43, v50 offset0:144 offset1:212
	v_cvt_pk_bf16_f32 v43, v46, v47
	v_exp_f32_e32 v46, v44
	v_exp_f32_e32 v47, v45
	v_add_u32_e32 v130, 0xa800, v97
	ds_write2_b32 v130, v127, v43 offset0:16 offset1:84
	v_min_f32_e64 v43, -v44, s33
	v_exp_f32_e32 v44, v43
	v_min_f32_e64 v43, -v45, s33
	v_lshlrev_b32_e32 v50, 16, v83
	v_and_b32_e32 v51, 0xffff0000, v83
	v_exp_f32_e32 v45, v43
	v_pk_mul_f32 v[46:47], v[46:47], v[50:51]
	v_pk_add_f32 v[40:41], v[40:41], v[58:59]
	v_cvt_pk_bf16_f32 v127, v46, v47
	v_exp_f32_e32 v46, v40
	v_min_f32_e64 v40, -v40, s33
	v_exp_f32_e32 v47, v41
	v_min_f32_e64 v41, -v41, s33
	v_exp_f32_e32 v40, v40
	v_exp_f32_e32 v41, v41
	v_lshlrev_b32_e32 v50, 16, v84
	v_and_b32_e32 v51, 0xffff0000, v84
	v_pk_mul_f32 v[44:45], v[44:45], v[50:51]
	s_waitcnt vmcnt(33)
	v_lshlrev_b32_e32 v50, 16, v86
	v_and_b32_e32 v51, 0xffff0000, v86
	v_pk_mul_f32 v[46:47], v[46:47], v[50:51]
	s_waitcnt vmcnt(32)
	v_lshlrev_b32_e32 v50, 16, v87
	v_and_b32_e32 v51, 0xffff0000, v87
	v_pk_mul_f32 v[40:41], v[40:41], v[50:51]
	v_mov_b32_e32 v50, v44
	v_mov_b32_e32 v51, v40
	v_pk_mul_f32 v[128:129], v[38:39], v[128:129] op_sel_hi:[0,1]
	v_pk_mul_f32 v[60:61], v[38:39], v[60:61] op_sel_hi:[0,1]
	v_pk_mul_f32 v[54:55], v[38:39], v[54:55] op_sel_hi:[0,1]
	v_pk_mul_f32 v[50:51], v[38:39], v[50:51] op_sel_hi:[0,1]
	v_mov_b32_e32 v38, v45
	v_mov_b32_e32 v39, v41
	v_pk_mul_f32 v[42:43], v[42:43], v[38:39] op_sel_hi:[0,1]
	v_cvt_pk_bf16_f32 v38, v46, v47
	v_add_u32_e32 v39, 0x8800, v97
	v_cvt_pk_bf16_f32 v131, v44, v45
	ds_write2_b32 v39, v127, v38 offset0:24 offset1:92
	v_cvt_pk_bf16_f32 v38, v40, v41
	ds_write2_b32 v130, v131, v38 offset0:152 offset1:220
	v_cvt_pk_bf16_f32 v38, v128, v129
	v_cvt_pk_bf16_f32 v39, v60, v61
	v_cvt_pk_bf16_f32 v40, v54, v55
	v_cvt_pk_bf16_f32 v41, v50, v51
	s_cmp_gt_u32 s18, 5
	ds_write_b128 v93, v[38:41] offset:50688
	v_cvt_pk_bf16_f32 v38, v56, v57
	v_cvt_pk_bf16_f32 v39, v52, v53
	v_cvt_pk_bf16_f32 v40, v48, v49
	v_cvt_pk_bf16_f32 v41, v42, v43
	s_cselect_b64 s[16:17], -1, 0
	ds_write_b128 v93, v[38:41] offset:50768
	s_waitcnt vmcnt(31)
	v_and_b32_e32 v38, 0xffff, v88
	s_waitcnt vmcnt(29)
	v_and_b32_e32 v39, 0xffff, v90
	v_lshrrev_b32_e32 v40, 16, v88
	v_lshrrev_b32_e32 v41, 16, v90
	v_lshl_or_b32 v38, v89, 16, v38
	s_waitcnt vmcnt(28)
	v_lshl_or_b32 v39, v91, 16, v39
	v_and_or_b32 v40, v89, s65, v40
	v_and_or_b32 v41, v91, s65, v41
	v_add_u32_e32 v42, 0xe800, v94
	s_and_b64 vcc, exec, s[16:17]
	ds_write2_b64 v42, v[38:39], v[40:41] offset0:192 offset1:202
	s_waitcnt lgkmcnt(0)
	s_barrier
	s_cbranch_vccnz .LBB0_554
	s_min_u32 s18, s18, 4
	s_add_i32 s18, s18, 3
	s_mul_i32 s18, s18, s57
	s_add_i32 s18, s18, s58
	s_ashr_i32 s19, s18, 31
	s_lshl_b64 s[20:21], s[18:19], 13
	s_add_u32 s22, s20, s61
	s_addc_u32 s23, s21, 0
	s_lshl_b64 s[22:23], s[22:23], 1
	s_add_u32 s22, s26, s22
	s_addc_u32 s23, s27, s23
	s_add_u32 s24, s20, s70
	s_addc_u32 s25, s21, 0
	s_lshl_b64 s[24:25], s[24:25], 1
	s_add_u32 s24, s26, s24
	s_addc_u32 s25, s27, s25
	s_add_u32 s20, s20, s96
	s_addc_u32 s21, s21, 0
	s_lshl_b64 s[20:21], s[20:21], 1
	s_mul_hi_i32 s19, s0, s18
	s_mul_i32 s18, s0, s18
	s_add_u32 s18, s54, s18
	s_addc_u32 s19, s55, s19
	global_load_dword v62, v144, s[18:19]
	global_load_dword v63, v36, s[22:23]
	global_load_dword v64, v36, s[24:25]
	global_load_dword v65, v32, s[18:19]
	global_load_dword v66, v34, s[22:23]
	global_load_dword v67, v34, s[24:25]
	global_load_dword v68, v28, s[18:19]
	global_load_dword v69, v30, s[22:23]
	global_load_dword v70, v30, s[24:25]
	global_load_dword v71, v24, s[18:19]
	global_load_dword v72, v26, s[22:23]
	global_load_dword v73, v26, s[24:25]
	global_load_dword v74, v20, s[18:19]
	global_load_dword v75, v22, s[22:23]
	global_load_dword v76, v22, s[24:25]
	global_load_dword v77, v16, s[18:19]
	global_load_dword v78, v18, s[22:23]
	global_load_dword v79, v18, s[24:25]
	global_load_dword v80, v12, s[18:19]
	global_load_dword v83, v14, s[22:23]
	global_load_dword v84, v14, s[24:25]
	global_load_dword v85, v8, s[18:19]
	s_add_u32 s18, s26, s20
	v_lshl_add_u64 v[38:39], s[22:23], 0, v[10:11]
	s_addc_u32 s19, s27, s21
	global_load_dword v86, v[38:39], off
	global_load_dword v87, v10, s[24:25]
	global_load_dword v88, v6, s[18:19]
	global_load_dword v89, v4, s[18:19]
	global_load_dword v90, v2, s[18:19]
	global_load_dword v91, v0, s[18:19]
	s_waitcnt vmcnt(55)
	v_lshlrev_b32_e32 v38, 16, v119
	v_and_b32_e32 v39, 0xffff0000, v119
	v_pk_fma_f32 v[56:57], v[38:39], s[66:67], 0 op_sel_hi:[1,0,0]
	s_waitcnt vmcnt(52)
	v_lshlrev_b32_e32 v38, 16, v120
	v_and_b32_e32 v39, 0xffff0000, v120
	v_pk_fma_f32 v[54:55], v[38:39], s[66:67], v[56:57] op_sel_hi:[1,0,1]
	s_waitcnt vmcnt(49)
	v_lshlrev_b32_e32 v38, 16, v121
	v_and_b32_e32 v39, 0xffff0000, v121
	v_pk_fma_f32 v[52:53], v[38:39], s[66:67], v[54:55] op_sel_hi:[1,0,1]
	s_waitcnt vmcnt(46)
	v_lshlrev_b32_e32 v38, 16, v122
	v_and_b32_e32 v39, 0xffff0000, v122
	v_pk_fma_f32 v[50:51], v[38:39], s[66:67], v[52:53] op_sel_hi:[1,0,1]
	s_waitcnt vmcnt(43)
	v_lshlrev_b32_e32 v38, 16, v123
	v_and_b32_e32 v39, 0xffff0000, v123
	v_pk_fma_f32 v[48:49], v[38:39], s[66:67], v[50:51] op_sel_hi:[1,0,1]
	s_waitcnt vmcnt(40)
	v_lshlrev_b32_e32 v38, 16, v124
	v_and_b32_e32 v39, 0xffff0000, v124
	v_pk_fma_f32 v[46:47], v[38:39], s[66:67], v[48:49] op_sel_hi:[1,0,1]
	s_waitcnt vmcnt(37)
	v_lshlrev_b32_e32 v38, 16, v125
	v_and_b32_e32 v39, 0xffff0000, v125
	v_pk_fma_f32 v[44:45], v[38:39], s[66:67], v[46:47] op_sel_hi:[1,0,1]
	s_waitcnt vmcnt(34)
	v_lshlrev_b32_e32 v38, 16, v126
	v_and_b32_e32 v39, 0xffff0000, v126
	v_pk_fma_f32 v[40:41], v[38:39], s[66:67], v[44:45] op_sel_hi:[1,0,1]
	ds_bpermute_b32 v60, v81, v40
	ds_bpermute_b32 v61, v81, v41
	s_waitcnt lgkmcnt(0)
	v_pk_add_f32 v[38:39], v[40:41], v[60:61]
	ds_bpermute_b32 v58, v82, v38
	ds_bpermute_b32 v59, v82, v39
	s_waitcnt lgkmcnt(0)
	v_pk_add_f32 v[42:43], v[38:39], v[58:59]
	s_nop 0
	v_exp_f32_e32 v38, v42
	s_and_saveexec_b64 s[18:19], s[10:11]
	s_xor_b64 s[18:19], exec, s[18:19]
	s_or_saveexec_b64 s[18:19], s[18:19]
	v_exp_f32_e32 v42, v43
	s_xor_b64 exec, exec, s[18:19]
	s_cbranch_execz .LBB0_553
	v_mov_b32_e32 v120, v38
	v_mov_b32_e32 v121, v42
	ds_write_b64 v98, v[120:121] offset:32768
	s_branch .LBB0_553

.LBB0_662:
	s_add_i32 s1, s18, 2
	s_min_u32 s9, s1, 0x7f
	s_mul_i32 s9, s9, s70
	v_readlane_b32 s16, v241, 46
	v_readlane_b32 s17, v241, 47
	s_add_i32 s16, s9, s16
	s_ashr_i32 s17, s16, 31
	s_lshl_b64 s[22:23], s[16:17], 13
	s_add_u32 s26, s22, s4
	s_addc_u32 s27, s23, 0
	s_lshl_b64 s[26:27], s[26:27], 1
	s_add_u32 s26, s20, s26
	s_addc_u32 s27, s21, s27
	s_add_u32 s28, s22, s5
	s_addc_u32 s29, s23, 0
	s_lshl_b64 s[28:29], s[28:29], 1
	s_add_u32 s28, s20, s28
	s_addc_u32 s29, s21, s29
	s_add_u32 s22, s22, s8
	s_addc_u32 s23, s23, 0
	s_lshl_b64 s[22:23], s[22:23], 1
	s_mul_hi_i32 s9, s0, s16
	s_mul_i32 s16, s0, s16
	s_add_u32 s16, s24, s16
	s_addc_u32 s17, s25, s9
	global_load_dword v119, v144, s[16:17]
	global_load_dword v118, v36, s[26:27]
	global_load_dword v117, v36, s[28:29]
	global_load_dword v120, v32, s[16:17]
	global_load_dword v116, v34, s[26:27]
	global_load_dword v115, v34, s[28:29]
	global_load_dword v121, v28, s[16:17]
	global_load_dword v114, v30, s[26:27]
	global_load_dword v113, v30, s[28:29]
	global_load_dword v122, v24, s[16:17]
	global_load_dword v112, v26, s[26:27]
	global_load_dword v111, v26, s[28:29]
	global_load_dword v123, v20, s[16:17]
	global_load_dword v110, v22, s[26:27]
	global_load_dword v109, v22, s[28:29]
	global_load_dword v124, v16, s[16:17]
	global_load_dword v108, v18, s[26:27]
	global_load_dword v107, v18, s[28:29]
	global_load_dword v125, v12, s[16:17]
	global_load_dword v106, v14, s[26:27]
	global_load_dword v105, v14, s[28:29]
	global_load_dword v126, v8, s[16:17]
	s_add_u32 s16, s20, s22
	v_lshl_add_u64 v[38:39], s[26:27], 0, v[10:11]
	s_addc_u32 s17, s21, s23
	global_load_dword v104, v[38:39], off
	global_load_dword v103, v10, s[28:29]
	global_load_dword v99, v6, s[16:17]
	global_load_dword v100, v4, s[16:17]
	global_load_dword v101, v2, s[16:17]
	global_load_dword v102, v0, s[16:17]
	s_waitcnt vmcnt(55)
	v_lshlrev_b32_e32 v38, 16, v62
	v_and_b32_e32 v39, 0xffff0000, v62
	v_pk_fma_f32 v[56:57], v[38:39], s[66:67], 0 op_sel_hi:[1,0,0]
	s_waitcnt vmcnt(52)
	v_lshlrev_b32_e32 v38, 16, v65
	v_and_b32_e32 v39, 0xffff0000, v65
	v_pk_fma_f32 v[54:55], v[38:39], s[66:67], v[56:57] op_sel_hi:[1,0,1]
	s_waitcnt vmcnt(49)
	v_lshlrev_b32_e32 v38, 16, v68
	v_and_b32_e32 v39, 0xffff0000, v68
	v_pk_fma_f32 v[52:53], v[38:39], s[66:67], v[54:55] op_sel_hi:[1,0,1]
	s_waitcnt vmcnt(46)
	v_lshlrev_b32_e32 v38, 16, v71
	v_and_b32_e32 v39, 0xffff0000, v71
	v_pk_fma_f32 v[50:51], v[38:39], s[66:67], v[52:53] op_sel_hi:[1,0,1]
	s_waitcnt vmcnt(43)
	v_lshlrev_b32_e32 v38, 16, v74
	v_and_b32_e32 v39, 0xffff0000, v74
	v_pk_fma_f32 v[48:49], v[38:39], s[66:67], v[50:51] op_sel_hi:[1,0,1]
	s_waitcnt vmcnt(40)
	v_lshlrev_b32_e32 v38, 16, v77
	v_and_b32_e32 v39, 0xffff0000, v77
	v_pk_fma_f32 v[46:47], v[38:39], s[66:67], v[48:49] op_sel_hi:[1,0,1]
	s_waitcnt vmcnt(37)
	v_lshlrev_b32_e32 v38, 16, v81
	v_and_b32_e32 v39, 0xffff0000, v81
	v_pk_fma_f32 v[44:45], v[38:39], s[66:67], v[46:47] op_sel_hi:[1,0,1]
	s_waitcnt vmcnt(34)
	v_lshlrev_b32_e32 v38, 16, v85
	v_and_b32_e32 v39, 0xffff0000, v85
	v_pk_fma_f32 v[40:41], v[38:39], s[66:67], v[44:45] op_sel_hi:[1,0,1]
	ds_bpermute_b32 v60, v80, v40
	ds_bpermute_b32 v61, v80, v41
	s_waitcnt lgkmcnt(0)
	v_pk_add_f32 v[38:39], v[40:41], v[60:61]
	ds_bpermute_b32 v58, v82, v38
	ds_bpermute_b32 v59, v82, v39
	s_waitcnt lgkmcnt(0)
	v_pk_add_f32 v[42:43], v[38:39], v[58:59]
	s_nop 0
	v_exp_f32_e32 v38, v42
	s_and_saveexec_b64 s[16:17], s[10:11]
	s_xor_b64 s[16:17], exec, s[16:17]
	s_or_saveexec_b64 s[16:17], s[16:17]
	v_exp_f32_e32 v42, v43
	s_xor_b64 exec, exec, s[16:17]
	v_mov_b32_e32 v128, v38
	v_mov_b32_e32 v129, v42
	ds_write_b64 v96, v[128:129]
	s_or_b64 exec, exec, s[16:17]
	v_pk_add_f32 v[60:61], v[60:61], 0 op_sel_hi:[1,0]
	v_lshlrev_b32_e32 v128, 16, v63
	v_cndmask_b32_e64 v61, v61, 0, s[12:13]
	v_cndmask_b32_e64 v60, v60, 0, s[12:13]
	v_pk_add_f32 v[58:59], v[60:61], v[58:59]
	v_and_b32_e32 v129, 0xffff0000, v63
	v_cndmask_b32_e64 v59, v59, v61, s[14:15]
	v_cndmask_b32_e64 v58, v58, v60, s[14:15]
	v_pk_add_f32 v[56:57], v[56:57], v[58:59]
	v_pk_add_f32 v[54:55], v[54:55], v[58:59]
	v_exp_f32_e32 v60, v56
	v_exp_f32_e32 v61, v57
	v_min_f32_e64 v43, -v56, s33
	v_exp_f32_e32 v56, v43
	v_min_f32_e64 v43, -v57, s33
	v_exp_f32_e32 v57, v43
	v_pk_mul_f32 v[60:61], v[60:61], v[128:129]
	v_lshlrev_b32_e32 v128, 16, v64
	v_cvt_pk_bf16_f32 v43, v60, v61
	v_exp_f32_e32 v60, v54
	v_min_f32_e64 v54, -v54, s33
	v_exp_f32_e32 v61, v55
	v_min_f32_e64 v55, -v55, s33
	v_exp_f32_e32 v54, v54
	v_exp_f32_e32 v55, v55
	v_and_b32_e32 v129, 0xffff0000, v64
	v_pk_mul_f32 v[56:57], v[56:57], v[128:129]
	v_lshlrev_b32_e32 v128, 16, v66
	v_and_b32_e32 v129, 0xffff0000, v66
	v_pk_mul_f32 v[60:61], v[60:61], v[128:129]
	v_lshlrev_b32_e32 v128, 16, v67
	v_and_b32_e32 v129, 0xffff0000, v67
	v_pk_mul_f32 v[54:55], v[54:55], v[128:129]
	v_cvt_pk_bf16_f32 v127, v56, v57
	v_mov_b32_e32 v128, v56
	v_mov_b32_e32 v56, v57
	v_mov_b32_e32 v57, v55
	v_cvt_pk_bf16_f32 v60, v60, v61
	v_add_u32_e32 v61, 0x8000, v97
	v_pk_add_f32 v[52:53], v[52:53], v[58:59]
	v_mov_b32_e32 v129, v54
	v_pk_mul_f32 v[56:57], v[42:43], v[56:57] op_sel_hi:[0,1]
	ds_write2_b32 v61, v43, v60 offset0:128 offset1:196
	v_cvt_pk_bf16_f32 v43, v54, v55
	v_exp_f32_e32 v54, v52
	v_exp_f32_e32 v55, v53
	v_add_u32_e32 v130, 0xa400, v97
	ds_write2_b32 v130, v127, v43 offset1:68
	v_min_f32_e64 v43, -v52, s33
	v_exp_f32_e32 v52, v43
	v_min_f32_e64 v43, -v53, s33
	v_lshlrev_b32_e32 v60, 16, v69
	v_and_b32_e32 v61, 0xffff0000, v69
	v_exp_f32_e32 v53, v43
	v_pk_mul_f32 v[54:55], v[54:55], v[60:61]
	v_pk_add_f32 v[50:51], v[50:51], v[58:59]
	v_cvt_pk_bf16_f32 v43, v54, v55
	v_exp_f32_e32 v54, v50
	v_min_f32_e64 v50, -v50, s33
	v_exp_f32_e32 v55, v51
	v_min_f32_e64 v51, -v51, s33
	v_exp_f32_e32 v50, v50
	v_exp_f32_e32 v51, v51
	v_lshlrev_b32_e32 v60, 16, v70
	v_and_b32_e32 v61, 0xffff0000, v70
	v_pk_mul_f32 v[52:53], v[52:53], v[60:61]
	v_lshlrev_b32_e32 v60, 16, v72
	v_and_b32_e32 v61, 0xffff0000, v72
	v_pk_mul_f32 v[54:55], v[54:55], v[60:61]
	v_lshlrev_b32_e32 v60, 16, v73
	v_and_b32_e32 v61, 0xffff0000, v73
	v_pk_mul_f32 v[50:51], v[50:51], v[60:61]
	v_cvt_pk_bf16_f32 v127, v52, v53
	v_mov_b32_e32 v60, v52
	v_mov_b32_e32 v52, v53
	v_mov_b32_e32 v53, v51
	v_cvt_pk_bf16_f32 v54, v54, v55
	v_add_u32_e32 v131, 0x8400, v97
	v_pk_add_f32 v[48:49], v[48:49], v[58:59]
	v_mov_b32_e32 v61, v50
	v_pk_mul_f32 v[52:53], v[42:43], v[52:53] op_sel_hi:[0,1]
	ds_write2_b32 v131, v43, v54 offset0:8 offset1:76
	v_cvt_pk_bf16_f32 v43, v50, v51
	v_exp_f32_e32 v50, v48
	v_exp_f32_e32 v51, v49
	ds_write2_b32 v130, v127, v43 offset0:136 offset1:204
	v_min_f32_e64 v43, -v48, s33
	v_exp_f32_e32 v48, v43
	v_min_f32_e64 v43, -v49, s33
	v_lshlrev_b32_e32 v54, 16, v75
	v_and_b32_e32 v55, 0xffff0000, v75
	v_exp_f32_e32 v49, v43
	v_pk_mul_f32 v[50:51], v[50:51], v[54:55]
	v_pk_add_f32 v[46:47], v[46:47], v[58:59]
	v_cvt_pk_bf16_f32 v43, v50, v51
	v_exp_f32_e32 v50, v46
	v_min_f32_e64 v46, -v46, s33
	v_exp_f32_e32 v51, v47
	v_min_f32_e64 v47, -v47, s33
	v_exp_f32_e32 v46, v46
	v_exp_f32_e32 v47, v47
	v_lshlrev_b32_e32 v54, 16, v76
	v_and_b32_e32 v55, 0xffff0000, v76
	v_pk_mul_f32 v[48:49], v[48:49], v[54:55]
	v_lshlrev_b32_e32 v54, 16, v78
	v_and_b32_e32 v55, 0xffff0000, v78
	v_pk_mul_f32 v[50:51], v[50:51], v[54:55]
	v_lshlrev_b32_e32 v54, 16, v79
	v_and_b32_e32 v55, 0xffff0000, v79
	v_pk_mul_f32 v[46:47], v[46:47], v[54:55]
	v_cvt_pk_bf16_f32 v127, v48, v49
	v_mov_b32_e32 v54, v48
	v_mov_b32_e32 v48, v49
	v_mov_b32_e32 v49, v47
	v_cvt_pk_bf16_f32 v50, v50, v51
	v_pk_add_f32 v[44:45], v[44:45], v[58:59]
	v_mov_b32_e32 v55, v46
	v_pk_mul_f32 v[48:49], v[42:43], v[48:49] op_sel_hi:[0,1]
	ds_write2_b32 v131, v43, v50 offset0:144 offset1:212
	v_cvt_pk_bf16_f32 v43, v46, v47
	v_exp_f32_e32 v46, v44
	v_exp_f32_e32 v47, v45
	v_add_u32_e32 v130, 0xa800, v97
	ds_write2_b32 v130, v127, v43 offset0:16 offset1:84
	v_min_f32_e64 v43, -v44, s33
	v_exp_f32_e32 v44, v43
	v_min_f32_e64 v43, -v45, s33
	v_lshlrev_b32_e32 v50, 16, v83
	v_and_b32_e32 v51, 0xffff0000, v83
	v_exp_f32_e32 v45, v43
	v_pk_mul_f32 v[46:47], v[46:47], v[50:51]
	v_pk_add_f32 v[40:41], v[40:41], v[58:59]
	v_cvt_pk_bf16_f32 v127, v46, v47
	v_exp_f32_e32 v46, v40
	v_min_f32_e64 v40, -v40, s33
	v_exp_f32_e32 v47, v41
	v_min_f32_e64 v41, -v41, s33
	v_exp_f32_e32 v40, v40
	v_exp_f32_e32 v41, v41
	v_lshlrev_b32_e32 v50, 16, v84
	v_and_b32_e32 v51, 0xffff0000, v84
	v_pk_mul_f32 v[44:45], v[44:45], v[50:51]
	s_waitcnt vmcnt(33)
	v_lshlrev_b32_e32 v50, 16, v86
	v_and_b32_e32 v51, 0xffff0000, v86
	v_pk_mul_f32 v[46:47], v[46:47], v[50:51]
	s_waitcnt vmcnt(32)
	v_lshlrev_b32_e32 v50, 16, v87
	v_and_b32_e32 v51, 0xffff0000, v87
	v_pk_mul_f32 v[40:41], v[40:41], v[50:51]
	v_mov_b32_e32 v50, v44
	v_mov_b32_e32 v51, v40
	v_pk_mul_f32 v[128:129], v[38:39], v[128:129] op_sel_hi:[0,1]
	v_pk_mul_f32 v[60:61], v[38:39], v[60:61] op_sel_hi:[0,1]
	v_pk_mul_f32 v[54:55], v[38:39], v[54:55] op_sel_hi:[0,1]
	v_pk_mul_f32 v[50:51], v[38:39], v[50:51] op_sel_hi:[0,1]
	v_mov_b32_e32 v38, v45
	v_mov_b32_e32 v39, v41
	v_pk_mul_f32 v[42:43], v[42:43], v[38:39] op_sel_hi:[0,1]
	v_cvt_pk_bf16_f32 v38, v46, v47
	v_add_u32_e32 v39, 0x8800, v97
	v_cvt_pk_bf16_f32 v131, v44, v45
	ds_write2_b32 v39, v127, v38 offset0:24 offset1:92
	v_cvt_pk_bf16_f32 v38, v40, v41
	ds_write2_b32 v130, v131, v38 offset0:152 offset1:220
	v_cvt_pk_bf16_f32 v38, v128, v129
	v_cvt_pk_bf16_f32 v39, v60, v61
	v_cvt_pk_bf16_f32 v40, v54, v55
	v_cvt_pk_bf16_f32 v41, v50, v51
	s_cmpk_gt_u32 s18, 0x7d
	ds_write_b128 v93, v[38:41] offset:50688
	v_cvt_pk_bf16_f32 v38, v56, v57
	v_cvt_pk_bf16_f32 v39, v52, v53
	v_cvt_pk_bf16_f32 v40, v48, v49
	v_cvt_pk_bf16_f32 v41, v42, v43
	s_cselect_b64 s[16:17], -1, 0
	ds_write_b128 v93, v[38:41] offset:50768
	s_waitcnt vmcnt(31)
	v_and_b32_e32 v38, 0xffff, v88
	s_waitcnt vmcnt(29)
	v_and_b32_e32 v39, 0xffff, v90
	v_lshrrev_b32_e32 v40, 16, v88
	v_lshrrev_b32_e32 v41, 16, v90
	v_lshl_or_b32 v38, v89, 16, v38
	s_waitcnt vmcnt(28)
	v_lshl_or_b32 v39, v91, 16, v39
	v_and_or_b32 v40, v89, s65, v40
	v_and_or_b32 v41, v91, s65, v41
	v_add_u32_e32 v42, 0xe800, v94
	s_and_b64 vcc, exec, s[16:17]
	ds_write2_b64 v42, v[38:39], v[40:41] offset0:192 offset1:202
	s_waitcnt lgkmcnt(0)
	s_barrier
	s_cbranch_vccnz .LBB0_661
	s_min_u32 s9, s18, 0x7c
	s_add_i32 s9, s9, 3
	s_mul_i32 s9, s9, s70
	v_readlane_b32 s18, v241, 46
	v_readlane_b32 s19, v241, 47
	s_add_i32 s18, s9, s18
	s_ashr_i32 s19, s18, 31
	s_lshl_b64 s[22:23], s[18:19], 13
	s_add_u32 s26, s22, s4
	s_addc_u32 s27, s23, 0
	s_lshl_b64 s[26:27], s[26:27], 1
	s_add_u32 s26, s20, s26
	s_addc_u32 s27, s21, s27
	s_add_u32 s28, s22, s5
	s_addc_u32 s29, s23, 0
	s_lshl_b64 s[28:29], s[28:29], 1
	s_add_u32 s28, s20, s28
	s_addc_u32 s29, s21, s29
	s_add_u32 s22, s22, s8
	s_addc_u32 s23, s23, 0
	s_lshl_b64 s[22:23], s[22:23], 1
	s_mul_hi_i32 s9, s0, s18
	s_mul_i32 s18, s0, s18
	s_add_u32 s18, s24, s18
	s_addc_u32 s19, s25, s9
	global_load_dword v62, v144, s[18:19]
	global_load_dword v63, v36, s[26:27]
	global_load_dword v64, v36, s[28:29]
	global_load_dword v65, v32, s[18:19]
	global_load_dword v66, v34, s[26:27]
	global_load_dword v67, v34, s[28:29]
	global_load_dword v68, v28, s[18:19]
	global_load_dword v69, v30, s[26:27]
	global_load_dword v70, v30, s[28:29]
	global_load_dword v71, v24, s[18:19]
	global_load_dword v72, v26, s[26:27]
	global_load_dword v73, v26, s[28:29]
	global_load_dword v74, v20, s[18:19]
	global_load_dword v75, v22, s[26:27]
	global_load_dword v76, v22, s[28:29]
	global_load_dword v77, v16, s[18:19]
	global_load_dword v78, v18, s[26:27]
	global_load_dword v79, v18, s[28:29]
	global_load_dword v81, v12, s[18:19]
	global_load_dword v83, v14, s[26:27]
	global_load_dword v84, v14, s[28:29]
	global_load_dword v85, v8, s[18:19]
	s_add_u32 s18, s20, s22
	v_lshl_add_u64 v[38:39], s[26:27], 0, v[10:11]
	s_addc_u32 s19, s21, s23
	global_load_dword v86, v[38:39], off
	global_load_dword v87, v10, s[28:29]
	global_load_dword v88, v6, s[18:19]
	global_load_dword v89, v4, s[18:19]
	global_load_dword v90, v2, s[18:19]
	global_load_dword v91, v0, s[18:19]
	s_waitcnt vmcnt(55)
	v_lshlrev_b32_e32 v38, 16, v119
	v_and_b32_e32 v39, 0xffff0000, v119
	v_pk_fma_f32 v[56:57], v[38:39], s[66:67], 0 op_sel_hi:[1,0,0]
	s_waitcnt vmcnt(52)
	v_lshlrev_b32_e32 v38, 16, v120
	v_and_b32_e32 v39, 0xffff0000, v120
	v_pk_fma_f32 v[54:55], v[38:39], s[66:67], v[56:57] op_sel_hi:[1,0,1]
	s_waitcnt vmcnt(49)
	v_lshlrev_b32_e32 v38, 16, v121
	v_and_b32_e32 v39, 0xffff0000, v121
	v_pk_fma_f32 v[52:53], v[38:39], s[66:67], v[54:55] op_sel_hi:[1,0,1]
	s_waitcnt vmcnt(46)
	v_lshlrev_b32_e32 v38, 16, v122
	v_and_b32_e32 v39, 0xffff0000, v122
	v_pk_fma_f32 v[50:51], v[38:39], s[66:67], v[52:53] op_sel_hi:[1,0,1]
	s_waitcnt vmcnt(43)
	v_lshlrev_b32_e32 v38, 16, v123
	v_and_b32_e32 v39, 0xffff0000, v123
	v_pk_fma_f32 v[48:49], v[38:39], s[66:67], v[50:51] op_sel_hi:[1,0,1]
	s_waitcnt vmcnt(40)
	v_lshlrev_b32_e32 v38, 16, v124
	v_and_b32_e32 v39, 0xffff0000, v124
	v_pk_fma_f32 v[46:47], v[38:39], s[66:67], v[48:49] op_sel_hi:[1,0,1]
	s_waitcnt vmcnt(37)
	v_lshlrev_b32_e32 v38, 16, v125
	v_and_b32_e32 v39, 0xffff0000, v125
	v_pk_fma_f32 v[44:45], v[38:39], s[66:67], v[46:47] op_sel_hi:[1,0,1]
	s_waitcnt vmcnt(34)
	v_lshlrev_b32_e32 v38, 16, v126
	v_and_b32_e32 v39, 0xffff0000, v126
	v_pk_fma_f32 v[40:41], v[38:39], s[66:67], v[44:45] op_sel_hi:[1,0,1]
	ds_bpermute_b32 v60, v80, v40
	ds_bpermute_b32 v61, v80, v41
	s_waitcnt lgkmcnt(0)
	v_pk_add_f32 v[38:39], v[40:41], v[60:61]
	ds_bpermute_b32 v58, v82, v38
	ds_bpermute_b32 v59, v82, v39
	s_waitcnt lgkmcnt(0)
	v_pk_add_f32 v[42:43], v[38:39], v[58:59]
	s_nop 0
	v_exp_f32_e32 v38, v42
	s_and_saveexec_b64 s[18:19], s[10:11]
	s_xor_b64 s[18:19], exec, s[18:19]
	s_or_saveexec_b64 s[18:19], s[18:19]
	v_exp_f32_e32 v42, v43
	s_xor_b64 exec, exec, s[18:19]
	s_cbranch_execz .LBB0_660
	v_mov_b32_e32 v120, v38
	v_mov_b32_e32 v121, v42
	ds_write_b64 v98, v[120:121] offset:32768
	s_branch .LBB0_660
